# Hyena Toeplitz blocks: skip the out-of-range zero-masking (16 v_cndmask per block) when the whole wave is in range
# speedup vs baseline: 1.0121x; 1.0005x over previous
; __device__ __forceinline__ void hyena_item(const Ctx& C, ArgsP a, int ly, int c, bf16_t* yout) {
;     ...
;             for (int dd = 0; dd < DG; ++dd) { const int d = dlo + dd; if (d == -64) continue;
;                 const bf16_t* Wd = Wb + abase + 128 * (DG - 1 - dd);
;                 bf16x8 fa[10];
; #pragma unroll
;                 for (int q = 0; q < 10; ++q) fa[q] = *(const bf16x8*)(Wd + 16 * (q - 3));
;                 if (d <= 15) HY_MMA(0)
;                 if (d >= -47 && d <= 31) HY_MMA(1)
;                 if (d >= -31 && d <= 47) HY_MMA(2)
;                 if (d >= -15) HY_MMA(3)
.LBB0_859:
	v_add_co_u32_e32 v211, vcc, 64, v210
	s_nop 1
	v_cndmask_b32_e32 v211, 0, v211, vcc
	v_add_u32_e32 v211, s80, v211
	v_mad_u64_u32 v[224:225], s[92:93], v211, s78, v[108:109]
	ds_read_b128 v[212:215], v224
	ds_read_b128 v[216:219], v224 offset:64
	ds_read_b128 v[220:223], v224 offset:128
	ds_read_b128 v[224:227], v224 offset:192
	s_setprio 1
	s_cmp_eq_u64 vcc, exec
	s_cbranch_scc1 .Lhy_fast_859
	s_waitcnt lgkmcnt(3)
	v_cndmask_b32_e32 v215, 0, v215, vcc
	v_cndmask_b32_e32 v214, 0, v214, vcc
	v_cndmask_b32_e32 v213, 0, v213, vcc
	v_cndmask_b32_e32 v212, 0, v212, vcc
	s_nop 1
	v_mfma_f32_16x16x32_bf16 v[62:65], v[94:97], v[212:215], v[62:65]
	v_mfma_f32_16x16x32_bf16 v[58:61], v[90:93], v[212:215], v[58:61]
	v_mfma_f32_16x16x32_bf16 v[54:57], v[98:101], v[212:215], v[54:57]
	v_mfma_f32_16x16x32_bf16 v[50:53], v[102:105], v[212:215], v[50:53]
	s_waitcnt lgkmcnt(2)
	v_cndmask_b32_e32 v215, 0, v219, vcc
	v_cndmask_b32_e32 v214, 0, v218, vcc
	v_cndmask_b32_e32 v213, 0, v217, vcc
	v_cndmask_b32_e32 v212, 0, v216, vcc
	s_nop 1
	v_mfma_f32_16x16x32_bf16 v[62:65], v[82:85], v[212:215], v[62:65]
	v_mfma_f32_16x16x32_bf16 v[58:61], v[74:77], v[212:215], v[58:61]
	v_mfma_f32_16x16x32_bf16 v[54:57], v[94:97], v[212:215], v[54:57]
	v_mfma_f32_16x16x32_bf16 v[50:53], v[90:93], v[212:215], v[50:53]
	s_waitcnt lgkmcnt(1)
	v_cndmask_b32_e32 v215, 0, v223, vcc
	v_cndmask_b32_e32 v214, 0, v222, vcc
	v_cndmask_b32_e32 v213, 0, v221, vcc
	v_cndmask_b32_e32 v212, 0, v220, vcc
	s_nop 1
	v_mfma_f32_16x16x32_bf16 v[62:65], v[70:73], v[212:215], v[62:65]
	v_mfma_f32_16x16x32_bf16 v[58:61], v[66:69], v[212:215], v[58:61]
	v_mfma_f32_16x16x32_bf16 v[54:57], v[82:85], v[212:215], v[54:57]
	v_mfma_f32_16x16x32_bf16 v[50:53], v[74:77], v[212:215], v[50:53]
	s_waitcnt lgkmcnt(0)
	v_cndmask_b32_e32 v215, 0, v227, vcc
	v_cndmask_b32_e32 v214, 0, v226, vcc
	v_cndmask_b32_e32 v213, 0, v225, vcc
	v_cndmask_b32_e32 v212, 0, v224, vcc
	s_nop 1
	v_mfma_f32_16x16x32_bf16 v[62:65], v[86:89], v[212:215], v[62:65]
	v_mfma_f32_16x16x32_bf16 v[58:61], v[78:81], v[212:215], v[58:61]
	v_mfma_f32_16x16x32_bf16 v[54:57], v[70:73], v[212:215], v[54:57]
	v_mfma_f32_16x16x32_bf16 v[50:53], v[66:69], v[212:215], v[50:53]
	s_setprio 0
.Lhy_join_859:
	s_cmpk_gt_u32 s57, 0x4e
	s_cbranch_scc1 .LBB0_857
.LBB0_860:
	v_add_u32_e32 v211, 0x50, v210
	v_cmp_gt_u32_e32 vcc, 64, v211
	s_nop 1
	v_cndmask_b32_e32 v211, 0, v211, vcc
	v_add_u32_e32 v211, s80, v211
	v_mad_u64_u32 v[224:225], s[92:93], v211, s78, v[108:109]
	ds_read_b128 v[212:215], v224
	ds_read_b128 v[216:219], v224 offset:64
	ds_read_b128 v[220:223], v224 offset:128
	ds_read_b128 v[224:227], v224 offset:192
	s_setprio 1
	s_cmp_eq_u64 vcc, exec
	s_cbranch_scc1 .Lhy_fast_860
	s_waitcnt lgkmcnt(3)
	v_cndmask_b32_e32 v215, 0, v215, vcc
	v_cndmask_b32_e32 v214, 0, v214, vcc
	v_cndmask_b32_e32 v213, 0, v213, vcc
	v_cndmask_b32_e32 v212, 0, v212, vcc
	s_nop 1
	v_mfma_f32_16x16x32_bf16 v[46:49], v[94:97], v[212:215], v[46:49]
	v_mfma_f32_16x16x32_bf16 v[42:45], v[90:93], v[212:215], v[42:45]
	v_mfma_f32_16x16x32_bf16 v[38:41], v[98:101], v[212:215], v[38:41]
	v_mfma_f32_16x16x32_bf16 v[34:37], v[102:105], v[212:215], v[34:37]
	s_waitcnt lgkmcnt(2)
	v_cndmask_b32_e32 v215, 0, v219, vcc
	v_cndmask_b32_e32 v214, 0, v218, vcc
	v_cndmask_b32_e32 v213, 0, v217, vcc
	v_cndmask_b32_e32 v212, 0, v216, vcc
	s_nop 1
	v_mfma_f32_16x16x32_bf16 v[46:49], v[82:85], v[212:215], v[46:49]
	v_mfma_f32_16x16x32_bf16 v[42:45], v[74:77], v[212:215], v[42:45]
	v_mfma_f32_16x16x32_bf16 v[38:41], v[94:97], v[212:215], v[38:41]
	v_mfma_f32_16x16x32_bf16 v[34:37], v[90:93], v[212:215], v[34:37]
	s_waitcnt lgkmcnt(1)
	v_cndmask_b32_e32 v215, 0, v223, vcc
	v_cndmask_b32_e32 v214, 0, v222, vcc
	v_cndmask_b32_e32 v213, 0, v221, vcc
	v_cndmask_b32_e32 v212, 0, v220, vcc
	s_nop 1
	v_mfma_f32_16x16x32_bf16 v[46:49], v[70:73], v[212:215], v[46:49]
	v_mfma_f32_16x16x32_bf16 v[42:45], v[66:69], v[212:215], v[42:45]
	v_mfma_f32_16x16x32_bf16 v[38:41], v[82:85], v[212:215], v[38:41]
	v_mfma_f32_16x16x32_bf16 v[34:37], v[74:77], v[212:215], v[34:37]
	s_waitcnt lgkmcnt(0)
	v_cndmask_b32_e32 v215, 0, v227, vcc
	v_cndmask_b32_e32 v214, 0, v226, vcc
	v_cndmask_b32_e32 v213, 0, v225, vcc
	v_cndmask_b32_e32 v212, 0, v224, vcc
	s_nop 1
	v_mfma_f32_16x16x32_bf16 v[46:49], v[86:89], v[212:215], v[46:49]
	v_mfma_f32_16x16x32_bf16 v[42:45], v[78:81], v[212:215], v[42:45]
	v_mfma_f32_16x16x32_bf16 v[38:41], v[70:73], v[212:215], v[38:41]
	v_mfma_f32_16x16x32_bf16 v[34:37], v[66:69], v[212:215], v[34:37]
	s_setprio 0
.Lhy_join_860:
	s_add_i32 s7, s57, -16
	s_cmpk_gt_u32 s7, 0x4e
	s_cbranch_scc1 .LBB0_858
.LBB0_861:
	v_add_u32_e32 v211, 0x60, v210
	v_cmp_gt_u32_e32 vcc, 64, v211
	s_nop 1
	v_cndmask_b32_e32 v211, 0, v211, vcc
	v_add_u32_e32 v211, s80, v211
	v_mad_u64_u32 v[224:225], s[92:93], v211, s78, v[108:109]
	ds_read_b128 v[212:215], v224
	ds_read_b128 v[216:219], v224 offset:64
	ds_read_b128 v[220:223], v224 offset:128
	ds_read_b128 v[224:227], v224 offset:192
	s_setprio 1
	s_cmp_eq_u64 vcc, exec
	s_cbranch_scc1 .Lhy_fast_861
	s_waitcnt lgkmcnt(3)
	v_cndmask_b32_e32 v215, 0, v215, vcc
	v_cndmask_b32_e32 v214, 0, v214, vcc
	v_cndmask_b32_e32 v213, 0, v213, vcc
	v_cndmask_b32_e32 v212, 0, v212, vcc
	s_nop 1
	v_mfma_f32_16x16x32_bf16 v[30:33], v[94:97], v[212:215], v[30:33]
	v_mfma_f32_16x16x32_bf16 v[26:29], v[90:93], v[212:215], v[26:29]
	v_mfma_f32_16x16x32_bf16 v[22:25], v[98:101], v[212:215], v[22:25]
	v_mfma_f32_16x16x32_bf16 v[18:21], v[102:105], v[212:215], v[18:21]
	s_waitcnt lgkmcnt(2)
	v_cndmask_b32_e32 v215, 0, v219, vcc
	v_cndmask_b32_e32 v214, 0, v218, vcc
	v_cndmask_b32_e32 v213, 0, v217, vcc
	v_cndmask_b32_e32 v212, 0, v216, vcc
	s_nop 1
	v_mfma_f32_16x16x32_bf16 v[30:33], v[82:85], v[212:215], v[30:33]
	v_mfma_f32_16x16x32_bf16 v[26:29], v[74:77], v[212:215], v[26:29]
	v_mfma_f32_16x16x32_bf16 v[22:25], v[94:97], v[212:215], v[22:25]
	v_mfma_f32_16x16x32_bf16 v[18:21], v[90:93], v[212:215], v[18:21]
	s_waitcnt lgkmcnt(1)
	v_cndmask_b32_e32 v215, 0, v223, vcc
	v_cndmask_b32_e32 v214, 0, v222, vcc
	v_cndmask_b32_e32 v213, 0, v221, vcc
	v_cndmask_b32_e32 v212, 0, v220, vcc
	s_nop 1
	v_mfma_f32_16x16x32_bf16 v[30:33], v[70:73], v[212:215], v[30:33]
	v_mfma_f32_16x16x32_bf16 v[26:29], v[66:69], v[212:215], v[26:29]
	v_mfma_f32_16x16x32_bf16 v[22:25], v[82:85], v[212:215], v[22:25]
	v_mfma_f32_16x16x32_bf16 v[18:21], v[74:77], v[212:215], v[18:21]
	s_waitcnt lgkmcnt(0)
	v_cndmask_b32_e32 v215, 0, v227, vcc
	v_cndmask_b32_e32 v214, 0, v226, vcc
	v_cndmask_b32_e32 v213, 0, v225, vcc
	v_cndmask_b32_e32 v212, 0, v224, vcc
	s_nop 1
	v_mfma_f32_16x16x32_bf16 v[30:33], v[86:89], v[212:215], v[30:33]
	v_mfma_f32_16x16x32_bf16 v[26:29], v[78:81], v[212:215], v[26:29]
	v_mfma_f32_16x16x32_bf16 v[22:25], v[70:73], v[212:215], v[22:25]
	v_mfma_f32_16x16x32_bf16 v[18:21], v[66:69], v[212:215], v[18:21]
	s_setprio 0

; __device__ __forceinline__ void hyena_item(const Ctx& C, ArgsP a, int ly, int c, bf16_t* yout) {
;     ...
;             for (int dd = 0; dd < DG; ++dd) { const int d = dlo + dd; if (d == -64) continue;
;                 const bf16_t* Wd = Wb + abase + 128 * (DG - 1 - dd);
;                 bf16x8 fa[10];
; #pragma unroll
;                 for (int q = 0; q < 10; ++q) fa[q] = *(const bf16x8*)(Wd + 16 * (q - 3));
;                 if (d <= 15) HY_MMA(0)
;                 if (d >= -47 && d <= 31) HY_MMA(1)
;                 if (d >= -31 && d <= 47) HY_MMA(2)
;                 if (d >= -15) HY_MMA(3)
.LBB0_862:
	v_add_u32_e32 v210, 0x70, v210
	v_cmp_gt_u32_e32 vcc, 64, v210
	s_nop 1
	v_cndmask_b32_e32 v210, 0, v210, vcc
	v_add_u32_e32 v210, s80, v210
	v_mad_u64_u32 v[222:223], s[6:7], v210, s78, v[108:109]
	ds_read_b128 v[210:213], v222
	ds_read_b128 v[214:217], v222 offset:64
	ds_read_b128 v[218:221], v222 offset:128
	ds_read_b128 v[222:225], v222 offset:192
	s_setprio 1
	s_cmp_eq_u64 vcc, exec
	s_cbranch_scc1 .Lhy_fast_862
	s_waitcnt lgkmcnt(3)
	v_cndmask_b32_e32 v213, 0, v213, vcc
	v_cndmask_b32_e32 v212, 0, v212, vcc
	v_cndmask_b32_e32 v211, 0, v211, vcc
	v_cndmask_b32_e32 v210, 0, v210, vcc
	s_nop 1
	v_mfma_f32_16x16x32_bf16 v[14:17], v[94:97], v[210:213], v[14:17]
	v_mfma_f32_16x16x32_bf16 v[10:13], v[90:93], v[210:213], v[10:13]
	v_mfma_f32_16x16x32_bf16 v[6:9], v[98:101], v[210:213], v[6:9]
	s_waitcnt lgkmcnt(2)
	v_cndmask_b32_e32 v101, 0, v217, vcc
	v_cndmask_b32_e32 v100, 0, v216, vcc
	v_cndmask_b32_e32 v99, 0, v215, vcc
	v_mfma_f32_16x16x32_bf16 v[2:5], v[102:105], v[210:213], v[2:5]
	v_cndmask_b32_e32 v98, 0, v214, vcc
	s_nop 1
	v_mfma_f32_16x16x32_bf16 v[14:17], v[82:85], v[98:101], v[14:17]
	v_mfma_f32_16x16x32_bf16 v[10:13], v[74:77], v[98:101], v[10:13]
	v_mfma_f32_16x16x32_bf16 v[6:9], v[94:97], v[98:101], v[6:9]
	v_mfma_f32_16x16x32_bf16 v[2:5], v[90:93], v[98:101], v[2:5]
	s_waitcnt lgkmcnt(1)
	v_cndmask_b32_e32 v93, 0, v221, vcc
	v_cndmask_b32_e32 v92, 0, v220, vcc
	v_cndmask_b32_e32 v91, 0, v219, vcc
	v_cndmask_b32_e32 v90, 0, v218, vcc
	s_nop 1
	v_mfma_f32_16x16x32_bf16 v[14:17], v[70:73], v[90:93], v[14:17]
	v_mfma_f32_16x16x32_bf16 v[10:13], v[66:69], v[90:93], v[10:13]
	v_mfma_f32_16x16x32_bf16 v[6:9], v[82:85], v[90:93], v[6:9]
	v_mfma_f32_16x16x32_bf16 v[2:5], v[74:77], v[90:93], v[2:5]
	s_waitcnt lgkmcnt(0)
	v_cndmask_b32_e32 v77, 0, v225, vcc
	v_cndmask_b32_e32 v76, 0, v224, vcc
	v_cndmask_b32_e32 v75, 0, v223, vcc
	v_cndmask_b32_e32 v74, 0, v222, vcc
	s_nop 1
	v_mfma_f32_16x16x32_bf16 v[14:17], v[86:89], v[74:77], v[14:17]
	v_mfma_f32_16x16x32_bf16 v[10:13], v[78:81], v[74:77], v[10:13]
	v_mfma_f32_16x16x32_bf16 v[6:9], v[70:73], v[74:77], v[6:9]
	v_mfma_f32_16x16x32_bf16 v[2:5], v[66:69], v[74:77], v[2:5]
	s_setprio 0

.Lhy_fast_859:
	s_waitcnt lgkmcnt(3)
	v_mfma_f32_16x16x32_bf16 v[62:65], v[94:97], v[212:215], v[62:65]
	v_mfma_f32_16x16x32_bf16 v[58:61], v[90:93], v[212:215], v[58:61]
	v_mfma_f32_16x16x32_bf16 v[54:57], v[98:101], v[212:215], v[54:57]
	v_mfma_f32_16x16x32_bf16 v[50:53], v[102:105], v[212:215], v[50:53]
	s_waitcnt lgkmcnt(2)
	v_mfma_f32_16x16x32_bf16 v[62:65], v[82:85], v[216:219], v[62:65]
	v_mfma_f32_16x16x32_bf16 v[58:61], v[74:77], v[216:219], v[58:61]
	v_mfma_f32_16x16x32_bf16 v[54:57], v[94:97], v[216:219], v[54:57]
	v_mfma_f32_16x16x32_bf16 v[50:53], v[90:93], v[216:219], v[50:53]
	s_waitcnt lgkmcnt(1)
	v_mfma_f32_16x16x32_bf16 v[62:65], v[70:73], v[220:223], v[62:65]
	v_mfma_f32_16x16x32_bf16 v[58:61], v[66:69], v[220:223], v[58:61]
	v_mfma_f32_16x16x32_bf16 v[54:57], v[82:85], v[220:223], v[54:57]
	v_mfma_f32_16x16x32_bf16 v[50:53], v[74:77], v[220:223], v[50:53]
	s_waitcnt lgkmcnt(0)
	v_mfma_f32_16x16x32_bf16 v[62:65], v[86:89], v[224:227], v[62:65]
	v_mfma_f32_16x16x32_bf16 v[58:61], v[78:81], v[224:227], v[58:61]
	v_mfma_f32_16x16x32_bf16 v[54:57], v[70:73], v[224:227], v[54:57]
	v_mfma_f32_16x16x32_bf16 v[50:53], v[66:69], v[224:227], v[50:53]
	s_setprio 0
	s_branch .Lhy_join_859
.Lhy_fast_860:
	s_waitcnt lgkmcnt(3)
	v_mfma_f32_16x16x32_bf16 v[46:49], v[94:97], v[212:215], v[46:49]
	v_mfma_f32_16x16x32_bf16 v[42:45], v[90:93], v[212:215], v[42:45]
	v_mfma_f32_16x16x32_bf16 v[38:41], v[98:101], v[212:215], v[38:41]
	v_mfma_f32_16x16x32_bf16 v[34:37], v[102:105], v[212:215], v[34:37]
	s_waitcnt lgkmcnt(2)
	v_mfma_f32_16x16x32_bf16 v[46:49], v[82:85], v[216:219], v[46:49]
	v_mfma_f32_16x16x32_bf16 v[42:45], v[74:77], v[216:219], v[42:45]
	v_mfma_f32_16x16x32_bf16 v[38:41], v[94:97], v[216:219], v[38:41]
	v_mfma_f32_16x16x32_bf16 v[34:37], v[90:93], v[216:219], v[34:37]
	s_waitcnt lgkmcnt(1)
	v_mfma_f32_16x16x32_bf16 v[46:49], v[70:73], v[220:223], v[46:49]
	v_mfma_f32_16x16x32_bf16 v[42:45], v[66:69], v[220:223], v[42:45]
	v_mfma_f32_16x16x32_bf16 v[38:41], v[82:85], v[220:223], v[38:41]
	v_mfma_f32_16x16x32_bf16 v[34:37], v[74:77], v[220:223], v[34:37]
	s_waitcnt lgkmcnt(0)
	v_mfma_f32_16x16x32_bf16 v[46:49], v[86:89], v[224:227], v[46:49]
	v_mfma_f32_16x16x32_bf16 v[42:45], v[78:81], v[224:227], v[42:45]
	v_mfma_f32_16x16x32_bf16 v[38:41], v[70:73], v[224:227], v[38:41]
	v_mfma_f32_16x16x32_bf16 v[34:37], v[66:69], v[224:227], v[34:37]
	s_setprio 0
	s_branch .Lhy_join_860
.Lhy_fast_861:
	s_waitcnt lgkmcnt(3)
	v_mfma_f32_16x16x32_bf16 v[30:33], v[94:97], v[212:215], v[30:33]
	v_mfma_f32_16x16x32_bf16 v[26:29], v[90:93], v[212:215], v[26:29]
	v_mfma_f32_16x16x32_bf16 v[22:25], v[98:101], v[212:215], v[22:25]
	v_mfma_f32_16x16x32_bf16 v[18:21], v[102:105], v[212:215], v[18:21]
	s_waitcnt lgkmcnt(2)
	v_mfma_f32_16x16x32_bf16 v[30:33], v[82:85], v[216:219], v[30:33]
	v_mfma_f32_16x16x32_bf16 v[26:29], v[74:77], v[216:219], v[26:29]
	v_mfma_f32_16x16x32_bf16 v[22:25], v[94:97], v[216:219], v[22:25]
	v_mfma_f32_16x16x32_bf16 v[18:21], v[90:93], v[216:219], v[18:21]
	s_waitcnt lgkmcnt(1)
	v_mfma_f32_16x16x32_bf16 v[30:33], v[70:73], v[220:223], v[30:33]
	v_mfma_f32_16x16x32_bf16 v[26:29], v[66:69], v[220:223], v[26:29]
	v_mfma_f32_16x16x32_bf16 v[22:25], v[82:85], v[220:223], v[22:25]
	v_mfma_f32_16x16x32_bf16 v[18:21], v[74:77], v[220:223], v[18:21]
	s_waitcnt lgkmcnt(0)
	v_mfma_f32_16x16x32_bf16 v[30:33], v[86:89], v[224:227], v[30:33]
	v_mfma_f32_16x16x32_bf16 v[26:29], v[78:81], v[224:227], v[26:29]
	v_mfma_f32_16x16x32_bf16 v[22:25], v[70:73], v[224:227], v[22:25]
	v_mfma_f32_16x16x32_bf16 v[18:21], v[66:69], v[224:227], v[18:21]
	s_setprio 0
	s_branch .Lhy_join_861
.Lhy_fast_862:
	s_waitcnt lgkmcnt(3)
	v_mfma_f32_16x16x32_bf16 v[14:17], v[94:97], v[210:213], v[14:17]
	v_mfma_f32_16x16x32_bf16 v[10:13], v[90:93], v[210:213], v[10:13]
	v_mfma_f32_16x16x32_bf16 v[6:9], v[98:101], v[210:213], v[6:9]
	s_waitcnt lgkmcnt(2)
	v_mfma_f32_16x16x32_bf16 v[2:5], v[102:105], v[210:213], v[2:5]
	v_mfma_f32_16x16x32_bf16 v[14:17], v[82:85], v[214:217], v[14:17]
	v_mfma_f32_16x16x32_bf16 v[10:13], v[74:77], v[214:217], v[10:13]
	v_mfma_f32_16x16x32_bf16 v[6:9], v[94:97], v[214:217], v[6:9]
	v_mfma_f32_16x16x32_bf16 v[2:5], v[90:93], v[214:217], v[2:5]
	s_waitcnt lgkmcnt(1)
	v_mfma_f32_16x16x32_bf16 v[14:17], v[70:73], v[218:221], v[14:17]
	v_mfma_f32_16x16x32_bf16 v[10:13], v[66:69], v[218:221], v[10:13]
	v_mfma_f32_16x16x32_bf16 v[6:9], v[82:85], v[218:221], v[6:9]
	v_mfma_f32_16x16x32_bf16 v[2:5], v[74:77], v[218:221], v[2:5]
	s_waitcnt lgkmcnt(0)
	v_mfma_f32_16x16x32_bf16 v[14:17], v[86:89], v[222:225], v[14:17]
	v_mfma_f32_16x16x32_bf16 v[10:13], v[78:81], v[222:225], v[10:13]
	v_mfma_f32_16x16x32_bf16 v[6:9], v[70:73], v[222:225], v[6:9]
	v_mfma_f32_16x16x32_bf16 v[2:5], v[66:69], v[222:225], v[2:5]
	s_setprio 0
	s_branch .Lhy_join_862
